# gMLP preamble: LayerNorm gain/bias load issued early, written to LDS right before the wave-unit loop (no wait + barrier in the preamble; the statistics-exchange barrier publishes it)
# baseline (speedup 1.0000x reference)
.Lgd_pre:
	global_load_dwordx4 v[212:215], v[2:3], off
	v_readlane_b32 s0, v251, 18
	s_add_i32 s16, s83, s0
	v_and_b32_e32 v157, 31, v200
	s_cmpk_gt_i32 s16, 0x7ff
	s_cbranch_scc1 .LBB0_126
	v_readlane_b32 s0, v255, 61
	s_nop 3
	s_bitcmp1_b32 s0, 0
	s_cbranch_scc1 .LBB0_126
	v_readlane_b32 s0, v252, 27
	v_lshrrev_b32_e32 v0, 5, v244
	v_readlane_b32 s0, v251, 23
	v_lshlrev_b32_e32 v1, 3, v0
	s_lshl_b64 s[0:1], s[94:95], 18
	v_readlane_b32 s2, v251, 21
	v_or_b32_e32 v3, 7, v1
	v_readlane_b32 s3, v251, 22
	s_add_u32 s0, s2, s0
	v_cmp_gt_u32_e64 s[84:85], v3, v157
	v_or_b32_e32 v3, 6, v1
	s_addc_u32 s1, s3, s1
	v_lshlrev_b32_e32 v192, 4, v0
	v_cmp_gt_u32_e64 s[86:87], v3, v157
	v_or_b32_e32 v3, 5, v1
	v_lshl_add_u64 v[158:159], s[0:1], 0, v[192:193]
	v_cmp_gt_u32_e64 s[0:1], v3, v157
	v_or_b32_e32 v3, 4, v1
	v_or_b32_e32 v2, 32, v244
	v_writelane_b32 v253, s0, 53
	v_readlane_b32 s4, v251, 4
	s_lshl_b64 s[2:3], s[94:95], 12
	v_writelane_b32 v253, s1, 54
	v_cmp_gt_u32_e64 s[0:1], v3, v157
	v_or_b32_e32 v3, 3, v1
	v_readlane_b32 s6, v251, 6
	v_writelane_b32 v253, s0, 55
	v_readlane_b32 s7, v251, 7
	s_add_u32 s12, s6, s2
	v_writelane_b32 v253, s1, 56
	v_cmp_gt_u32_e64 s[0:1], v3, v157
	v_or_b32_e32 v3, 2, v1
	s_mul_i32 s2, s83, 0x4400
	v_writelane_b32 v253, s0, 57
	s_addc_u32 s13, s7, s3
	s_add_i32 s2, s2, 0
	v_writelane_b32 v253, s1, 58
	v_cmp_gt_u32_e64 s[0:1], v3, v157
	v_or_b32_e32 v3, 23, v1
	v_add_u32_e32 v161, s2, v4
	v_writelane_b32 v253, s0, 59
	v_or_b32_e32 v4, 0x47, v1
	v_lshl_add_u32 v165, v0, 6, s2
	v_writelane_b32 v253, s1, 60
	v_cmp_lt_u32_e64 s[0:1], v1, v157
	v_and_b32_e32 v0, 7, v200
	v_add_u32_e32 v163, s2, v192
	v_writelane_b32 v253, s0, 61
	v_lshlrev_b32_e32 v167, 3, v0
	v_lshl_add_u32 v0, v0, 5, s2
	v_writelane_b32 v253, s1, 62
	v_cmp_gt_u32_e64 s[0:1], v3, v157
	v_or_b32_e32 v3, 22, v1
	s_lshl_b32 s14, s83, 6
	v_writelane_b32 v253, s0, 63
	v_readlane_b32 s5, v251, 5
	v_lshrrev_b32_e32 v160, 3, v244
	v_writelane_b32 v254, s1, 0
	v_cmp_gt_u32_e64 s[0:1], v3, v157
	v_or_b32_e32 v3, 21, v1
	v_readlane_b32 s8, v251, 8
	v_writelane_b32 v254, s0, 1
	v_readlane_b32 s9, v251, 9
	v_readlane_b32 s10, v251, 10
	v_writelane_b32 v254, s1, 2
	v_cmp_gt_u32_e64 s[0:1], v3, v157
	v_or_b32_e32 v3, 20, v1
	v_readlane_b32 s11, v251, 11
	v_writelane_b32 v254, s0, 3
	v_mul_u32_u24_e32 v171, 0x110, v2
	v_cmp_gt_u32_e64 s[52:53], v1, v157
	v_writelane_b32 v254, s1, 4
	v_cmp_gt_u32_e64 s[0:1], v3, v157
	v_or_b32_e32 v3, 19, v1
	v_readlane_b32 s36, v252, 13
	v_writelane_b32 v254, s0, 5
	v_readlane_b32 s80, v252, 17
	v_readlane_b32 s28, v252, 15
	v_writelane_b32 v254, s1, 6
	v_cmp_gt_u32_e64 s[0:1], v3, v157
	v_or_b32_e32 v3, 18, v1
	v_readlane_b32 s4, v252, 19
	v_writelane_b32 v254, s0, 7
	s_mov_b32 s27, s46
	v_lshlrev_b32_e32 v156, 1, v244
	v_writelane_b32 v254, s1, 8
	v_cmp_gt_u32_e64 s[0:1], v3, v157
	v_or_b32_e32 v3, 17, v1
	v_or_b32_e32 v162, 64, v160
	v_writelane_b32 v254, s0, 9
	v_mul_u32_u24_e32 v169, 0x110, v157
	v_or_b32_e32 v164, 8, v160
	v_writelane_b32 v254, s1, 10
	v_cmp_gt_u32_e64 s[0:1], v3, v157
	v_or_b32_e32 v3, 16, v1
	v_or_b32_e32 v166, 16, v160
	v_writelane_b32 v254, s0, 11
	v_or_b32_e32 v168, 24, v160
	v_or_b32_e32 v170, 32, v160
	v_writelane_b32 v254, s1, 12
	v_cmp_gt_u32_e64 s[0:1], v3, v157
	v_or_b32_e32 v3, 39, v1
	v_or_b32_e32 v172, 40, v160
	v_writelane_b32 v254, s0, 13
	v_or_b32_e32 v174, 48, v160
	v_or_b32_e32 v176, 56, v160
	v_writelane_b32 v254, s1, 14
	v_cmp_gt_u32_e64 s[0:1], v3, v2
	v_or_b32_e32 v3, 38, v1
	v_or_b32_e32 v178, 0x48, v160
	v_writelane_b32 v254, s0, 15
	v_or_b32_e32 v180, 0x50, v160
	v_or_b32_e32 v182, 0x58, v160
	v_writelane_b32 v254, s1, 16
	v_cmp_gt_u32_e64 s[0:1], v3, v2
	v_or_b32_e32 v3, 37, v1
	v_or_b32_e32 v184, 0x60, v160
	v_writelane_b32 v254, s0, 17
	v_or_b32_e32 v186, 0x68, v160
	v_or_b32_e32 v188, 0x70, v160
	v_writelane_b32 v254, s1, 18
	v_cmp_gt_u32_e64 s[0:1], v3, v2
	v_or_b32_e32 v3, 36, v1
	v_or_b32_e32 v190, 0x78, v160
	v_writelane_b32 v254, s0, 19
	v_readlane_b32 s37, v252, 14
	v_readlane_b32 s81, v252, 18
	v_writelane_b32 v254, s1, 20
	v_cmp_gt_u32_e64 s[0:1], v3, v2
	v_or_b32_e32 v3, 35, v1
	v_readlane_b32 s29, v252, 16
	v_writelane_b32 v254, s0, 21
	v_readlane_b32 s5, v252, 20
	v_readlane_b32 s23, v253, 12
	v_writelane_b32 v254, s1, 22
	v_cmp_gt_u32_e64 s[0:1], v3, v2
	v_or_b32_e32 v3, 34, v1
	s_movk_i32 s25, 0x4000
	v_writelane_b32 v254, s0, 23
	s_mov_b32 s44, 0x3a800000
	s_nop 0
	v_writelane_b32 v254, s1, 24
	v_cmp_gt_u32_e64 s[0:1], v3, v2
	v_or_b32_e32 v3, 33, v1
	s_nop 0
	v_writelane_b32 v254, s0, 25
	s_nop 1
	v_writelane_b32 v254, s1, 26
	v_cmp_gt_u32_e64 s[0:1], v3, v2
	v_or_b32_e32 v3, 32, v1
	s_nop 0
	v_writelane_b32 v254, s0, 27
	s_nop 1
	v_writelane_b32 v254, s1, 28
	v_cmp_gt_u32_e64 s[0:1], v3, v2
	v_or_b32_e32 v3, 55, v1
	s_nop 0
	v_writelane_b32 v254, s0, 29
	s_nop 1
	v_writelane_b32 v254, s1, 30
	v_cmp_gt_u32_e64 s[0:1], v3, v2
	v_or_b32_e32 v3, 54, v1
	s_nop 0
	v_writelane_b32 v254, s0, 31
	s_nop 1
	v_writelane_b32 v254, s1, 32
	v_cmp_gt_u32_e64 s[0:1], v3, v2
	v_or_b32_e32 v3, 53, v1
	s_nop 0
	v_writelane_b32 v254, s0, 33
	s_nop 1
	v_writelane_b32 v254, s1, 34
	v_cmp_gt_u32_e64 s[0:1], v3, v2
	v_or_b32_e32 v3, 52, v1
	s_nop 0
	v_writelane_b32 v254, s0, 35
	s_nop 1
	v_writelane_b32 v254, s1, 36
	v_cmp_gt_u32_e64 s[0:1], v3, v2
	v_or_b32_e32 v3, 51, v1
	s_nop 0
	v_writelane_b32 v254, s0, 37
	s_nop 1
	v_writelane_b32 v254, s1, 38
	v_cmp_gt_u32_e64 s[0:1], v3, v2
	v_or_b32_e32 v3, 50, v1
	s_nop 0
	v_writelane_b32 v254, s0, 39
	s_nop 1
	v_writelane_b32 v254, s1, 40
	v_cmp_gt_u32_e64 s[0:1], v3, v2
	v_or_b32_e32 v3, 49, v1
	s_nop 0
	v_writelane_b32 v254, s0, 41
	s_nop 1
	v_writelane_b32 v254, s1, 42
	v_cmp_gt_u32_e64 s[0:1], v3, v2
	v_or_b32_e32 v3, 48, v1
	s_nop 0
	v_writelane_b32 v254, s0, 43
	s_nop 1
	v_writelane_b32 v254, s1, 44
	v_cmp_gt_u32_e64 s[0:1], v3, v2
	v_or_b32_e32 v3, 64, v157
	v_mul_u32_u24_e32 v2, 0x110, v160
	v_writelane_b32 v254, s0, 45
	v_add_u32_e32 v173, v0, v2
	s_nop 0
	v_writelane_b32 v254, s1, 46
	v_cmp_gt_u32_e64 s[0:1], v4, v3
	v_or_b32_e32 v4, 0x46, v1
	s_nop 0
	v_writelane_b32 v254, s0, 47
	s_nop 1
	v_writelane_b32 v254, s1, 48
	v_cmp_gt_u32_e64 s[0:1], v4, v3
	v_or_b32_e32 v4, 0x45, v1
	s_nop 0
	v_writelane_b32 v254, s0, 49
	s_nop 1
	v_writelane_b32 v254, s1, 50
	v_cmp_gt_u32_e64 s[0:1], v4, v3
	v_or_b32_e32 v4, 0x44, v1
	s_nop 0
	v_writelane_b32 v254, s0, 51
	s_nop 1
	v_writelane_b32 v254, s1, 52
	v_cmp_gt_u32_e64 s[0:1], v4, v3
	v_or_b32_e32 v4, 0x43, v1
	s_nop 0
	v_writelane_b32 v254, s0, 53
	s_nop 1
	v_writelane_b32 v254, s1, 54
	v_cmp_gt_u32_e64 s[0:1], v4, v3
	v_or_b32_e32 v4, 0x42, v1
	s_nop 0
	v_writelane_b32 v254, s0, 55
	s_nop 1
	v_writelane_b32 v254, s1, 56
	v_cmp_gt_u32_e64 s[0:1], v4, v3
	v_or_b32_e32 v4, 0x41, v1
	s_nop 0
	v_writelane_b32 v254, s0, 57
	s_nop 1
	v_writelane_b32 v254, s1, 58
	v_cmp_gt_u32_e64 s[0:1], v4, v3
	v_or_b32_e32 v4, 0x57, v1
	s_nop 0
	v_writelane_b32 v254, s0, 59
	s_nop 1
	v_writelane_b32 v254, s1, 60
	v_cmp_gt_u32_e64 s[0:1], v4, v3
	v_or_b32_e32 v4, 0x56, v1
	s_nop 0
	v_writelane_b32 v254, s0, 61
	s_nop 1
	v_writelane_b32 v254, s1, 62
	v_cmp_gt_u32_e64 s[0:1], v4, v3
	v_or_b32_e32 v4, 0x55, v1
	s_nop 0
	v_writelane_b32 v254, s0, 63
	s_nop 1
	v_writelane_b32 v255, s1, 0
	v_cmp_gt_u32_e64 s[0:1], v4, v3
	v_or_b32_e32 v4, 0x54, v1
	s_nop 0
	v_writelane_b32 v255, s0, 1
	s_nop 1
	v_writelane_b32 v255, s1, 2
	v_cmp_gt_u32_e64 s[0:1], v4, v3
	v_or_b32_e32 v4, 0x53, v1
	s_nop 0
	v_writelane_b32 v255, s0, 3
	s_nop 1
	v_writelane_b32 v255, s1, 4
	v_cmp_gt_u32_e64 s[0:1], v4, v3
	v_or_b32_e32 v4, 0x52, v1
	s_nop 0
	v_writelane_b32 v255, s0, 5
	s_nop 1
	v_writelane_b32 v255, s1, 6
	v_cmp_gt_u32_e64 s[0:1], v4, v3
	v_or_b32_e32 v4, 0x51, v1
	s_nop 0
	v_writelane_b32 v255, s0, 7
	s_nop 1
	v_writelane_b32 v255, s1, 8
	v_cmp_gt_u32_e64 s[0:1], v4, v3
	v_or_b32_e32 v4, 0x50, v1
	s_nop 0
	v_writelane_b32 v255, s0, 9
	s_nop 1
	v_writelane_b32 v255, s1, 10
	v_cmp_gt_u32_e64 s[0:1], v4, v3
	v_or_b32_e32 v3, 0x60, v244
	v_or_b32_e32 v4, 0x67, v1
	v_writelane_b32 v255, s0, 11
	s_nop 1
	v_writelane_b32 v255, s1, 12
	v_cmp_gt_u32_e64 s[0:1], v4, v3
	v_or_b32_e32 v4, 0x66, v1
	s_nop 0
	v_writelane_b32 v255, s0, 13
	s_nop 1
	v_writelane_b32 v255, s1, 14
	v_cmp_gt_u32_e64 s[0:1], v4, v3
	v_or_b32_e32 v4, 0x65, v1
	s_nop 0
	v_writelane_b32 v255, s0, 15
	s_nop 1
	v_writelane_b32 v255, s1, 16
	v_cmp_gt_u32_e64 s[0:1], v4, v3
	v_or_b32_e32 v4, 0x64, v1
	s_nop 0
	v_writelane_b32 v255, s0, 17
	s_nop 1
	v_writelane_b32 v255, s1, 18
	v_cmp_gt_u32_e64 s[0:1], v4, v3
	v_or_b32_e32 v4, 0x63, v1
	s_nop 0
	v_writelane_b32 v255, s0, 19
	s_nop 1
	v_writelane_b32 v255, s1, 20
	v_cmp_gt_u32_e64 s[0:1], v4, v3
	v_or_b32_e32 v4, 0x62, v1
	s_nop 0
	v_writelane_b32 v255, s0, 21
	s_nop 1
	v_writelane_b32 v255, s1, 22
	v_cmp_gt_u32_e64 s[0:1], v4, v3
	v_or_b32_e32 v4, 0x61, v1
	s_nop 0
	v_writelane_b32 v255, s0, 23
	s_nop 1
	v_writelane_b32 v255, s1, 24
	v_cmp_gt_u32_e64 s[0:1], v4, v3
	v_or_b32_e32 v4, 0x60, v1
	s_nop 0
	v_writelane_b32 v255, s0, 25
	s_nop 1
	v_writelane_b32 v255, s1, 26
	v_cmp_gt_u32_e64 s[0:1], v4, v3
	v_or_b32_e32 v4, 0x77, v1
	s_nop 0
	v_writelane_b32 v255, s0, 27
	s_nop 1
	v_writelane_b32 v255, s1, 28
	v_cmp_gt_u32_e64 s[0:1], v4, v3
	v_or_b32_e32 v4, 0x76, v1
	s_nop 0
	v_writelane_b32 v255, s0, 29
	s_nop 1
	v_writelane_b32 v255, s1, 30
	v_cmp_gt_u32_e64 s[0:1], v4, v3
	v_or_b32_e32 v4, 0x75, v1
	s_nop 0
	v_writelane_b32 v255, s0, 31
	s_nop 1
	v_writelane_b32 v255, s1, 32
	v_cmp_gt_u32_e64 s[0:1], v4, v3
	v_or_b32_e32 v4, 0x74, v1
	v_cmp_gt_u32_e64 s[2:3], v4, v3
	v_writelane_b32 v255, s0, 33
	v_or_b32_e32 v4, 0x73, v1
	v_cmp_gt_u32_e64 s[40:41], v4, v3
	v_writelane_b32 v255, s1, 34
	v_readlane_b32 s0, v253, 10
	v_or_b32_e32 v4, 0x72, v1
	s_add_i32 s17, s0, s14
	s_lshl_b32 s14, s83, 3
	v_readlane_b32 s0, v253, 11
	v_cmp_gt_u32_e64 s[6:7], v4, v3
	v_or_b32_e32 v4, 0x71, v1
	v_or_b32_e32 v1, 0x70, v1
	s_add_i32 s18, s0, s14
	v_readlane_b32 s14, v253, 39
	v_readlane_b32 s0, v252, 21
	v_cmp_gt_u32_e64 s[8:9], v4, v3
	v_cmp_gt_u32_e64 s[10:11], v1, v3
	s_mov_b32 s26, s14
	v_readlane_b32 s1, v252, 22
	v_readlane_b32 s15, v253, 40
	v_lshlrev_b32_e32 v216, 4, v200
	v_add_u32_e32 v216, 0x22000, v216
	s_waitcnt vmcnt(0)
	ds_write_b128 v216, v[212:215]
